# chunkB loop: mixed-output tile collected in LDS and written as whole rows by the next step
# baseline (speedup 1.0000x reference)
; __device__ __forceinline__ void chunkB_item(const Args& A, LAS unsigned char* lds, int tid, int lane, int wave, int bh) {
;     ...
;     float* wo = A.out + OUT_WKVP + (size_t)bh * 4096;
; #pragma unroll
;     for (int nn = 0; nn < 2; ++nn)
; #pragma unroll
;         for (int jj = 0; jj < 4; ++jj) wo[(mt * 16 + q4 * 4 + jj) * 64 + (nt0 + nn) * 16 + fr] = acc[nn][jj];
.LBB0_268:
	s_waitcnt lgkmcnt(0)
	s_barrier
	s_lshl_b32 s42, s16, 11
	s_add_u32 s42, s42, s20
	s_add_u32 s42, s42, 0xde0000
	s_add_u32 s42, s96, s42
	s_addc_u32 s43, s97, 0
	ds_read_b64 v[24:25], v242 offset:34816
	ds_read_b64 v[26:27], v242 offset:35392
	s_waitcnt lgkmcnt(0)
	global_store_dwordx2 v234, v[24:25], s[42:43]
	global_store_dwordx2 v235, v[26:27], s[42:43]
	s_lshl_b64 s[12:13], s[12:13], 14
	s_add_u32 s12, s28, s12
	s_addc_u32 s13, s29, s13
	v_lshl_add_u32 v0, v92, 6, v96
	v_mov_b32_e32 v1, v95
	v_lshl_add_u64 v[0:1], v[0:1], 2, s[12:13]
	global_store_dword v[0:1], v16, off
	global_store_dword v[0:1], v17, off offset:256
	global_store_dword v[0:1], v18, off offset:512
	global_store_dword v[0:1], v19, off offset:768
	v_lshl_add_u32 v0, v92, 6, v106
	v_mov_b32_e32 v1, v95
	v_lshl_add_u64 v[0:1], v[0:1], 2, s[12:13]
	s_cmp_eq_u32 s38, 0
	global_store_dword v[0:1], v32, off
	global_store_dword v[0:1], v33, off offset:256
	global_store_dword v[0:1], v34, off offset:512
	global_store_dword v[0:1], v35, off offset:768
	s_cbranch_scc1 .LBB0_284

; #define LAS __attribute__((address_space(3)))
; __device__ __forceinline__ void chunkB_item(const Args& A, LAS unsigned char* lds, int tid, int lane, int wave, int bh) {
;     const int fr = lane & 15, q4 = lane >> 4, mt = wave >> 1, nt0 = (wave & 1) * 2, v0 = mt * 16 + q4 * 4;
;     const int h = bh & 7, b = bh >> 3, colg = h * 64 + v0;
;     const bf16_t* Z = (const bf16_t*)(A.ws + WS_Z); bf16_t* MIX = (bf16_t*)(A.ws + WS_XN);
;     LAS float* ST = (LAS float*)(lds + 18432);
;     f32x4 acc[2] = {{0.f, 0.f, 0.f, 0.f}, {0.f, 0.f, 0.f, 0.f}};
.LBB0_275:
	s_or_b64 exec, exec, s[12:13]
	v_mov_b32_e32 v0, s34
	s_waitcnt lgkmcnt(0)
	s_barrier
	ds_read_b32 v0, v0
	s_movk_i32 s13, 0x7f
	s_mov_b64 s[14:15], -1
	s_waitcnt lgkmcnt(0)
	s_barrier
	v_cmp_lt_i32_e32 vcc, s13, v0
	v_readfirstlane_b32 s12, v0
	s_cbranch_vccnz .LBB0_270
	s_lshr_b32 s98, s12, 3
	s_mul_i32 s98, s98, 0xe00000
	s_add_u32 s98, s94, s98
	s_addc_u32 s99, s95, 0
	s_sub_u32 s98, s98, 0x1c00
	s_subb_u32 s99, s99, 0
	v_lshrrev_b32_e32 v240, 4, v144
	v_lshrrev_b32_e32 v241, 6, v144
	v_lshl_add_u32 v240, v241, 2, v240
	v_and_b32_e32 v241, 15, v144
	v_mul_u32_u24_e32 v242, 0x90, v240
	v_lshl_add_u32 v242, v241, 3, v242
	v_add_u32_e32 v242, 0x6000, v242
	v_mul_u32_u24_e32 v240, 0x1c00, v240
	v_lshl_add_u32 v240, v241, 3, v240
	s_and_b32 s22, s12, 7
	s_lshl_b32 s22, s22, 7
	s_add_i32 s22, s22, 0x800
	v_add_u32_e32 v240, s22, v240
	v_add_u32_e32 v240, 0x1c00, v240
	v_add_u32_e32 v241, 0x7000, v240
	v_mul_u32_u24_e32 v243, 0x90, v96
	v_lshl_add_u32 v243, v92, 1, v243
	v_add_u32_e32 v243, 0x6000, v243
	global_load_dwordx2 v[182:183], v240, s[98:99]
	global_load_dwordx2 v[188:189], v241, s[98:99]
	global_load_dwordx2 v[184:185], v240, s[98:99] offset:1280
	global_load_dwordx2 v[190:191], v241, s[98:99] offset:1280
	s_and_b32 s38, s12, 7
	v_mov_b32_e32 v244, s38
	v_lshl_add_u32 v244, v244, 6, v92
	v_lshlrev_b32_e32 v244, 2, v244
	v_readlane_b32 s20, v249, 10
	v_readlane_b32 s21, v249, 11
	v_readlane_b32 s22, v249, 12
	v_readlane_b32 s23, v249, 13
	s_nop 4
	global_load_dwordx4 v[228:231], v244, s[20:21]
	global_load_dwordx4 v[250:253], v244, s[22:23]
	global_load_dwordx2 v[232:233], v244, s[6:7]
	global_load_dwordx2 v[254:255], v244, s[6:7] offset:8
	s_ashr_i32 s13, s12, 31
	s_mul_i32 s14, s12, 0xc0000
	s_mul_hi_i32 s15, s12, 0xc0000
	s_add_u32 s14, s86, s14
	s_addc_u32 s15, s87, s15
	s_add_u32 s16, s14, 0x2000
	v_lshlrev_b32_e32 v94, 8, v91
	v_lshl_add_u32 v94, v132, 4, v94
	v_lshrrev_b32_e32 v234, 4, v144
	v_lshrrev_b32_e32 v235, 6, v144
	v_lshl_add_u32 v234, v235, 2, v234
	v_lshlrev_b32_e32 v234, 11, v234
	v_and_b32_e32 v235, 15, v144
	v_lshl_add_u32 v234, v235, 3, v234
	v_mov_b32_e32 v235, s38
	v_lshl_add_u32 v234, v235, 7, v234
	v_add_u32_e32 v235, 0x2000, v234
	v_lshrrev_b32_e32 v236, 7, v144
	v_lshlrev_b32_e32 v236, 12, v236
	v_bfe_u32 v237, v144, 6, 1
	v_lshl_add_u32 v236, v237, 11, v236
	v_and_b32_e32 v237, 63, v144
	v_lshl_add_u32 v236, v237, 4, v236
	v_add_u32_e32 v236, 0x2000, v236
	v_add_u32_e32 v237, 0x400, v236
	v_add_u32_e32 v238, v148, v124
	v_add_u32_e32 v238, 0x2000, v238
	v_add_u32_e32 v239, v148, v126
	v_add_u32_e32 v239, 0x2000, v239
	v_mul_u32_u24_e32 v245, 0x1c00, v96
	v_lshl_add_u32 v245, v92, 1, v245
	v_mov_b32_e32 v246, s38
	v_lshl_add_u32 v245, v246, 7, v245
	v_add_u32_e32 v245, 0x800, v245
	v_lshlrev_b32_e32 v246, 4, v144
	v_bfe_u32 v247, v144, 6, 1
	v_lshlrev_b32_e32 v247, 12, v247
	v_and_b32_e32 v156, 63, v144
	v_lshl_add_u32 v247, v156, 4, v247
	global_load_dwordx4 v[210:213], v236, s[14:15]
	global_load_dwordx4 v[40:43], v237, s[14:15]
	global_load_dwordx4 v[0:3], v246, s[14:15]
	s_addc_u32 s17, s15, 0
	v_lshl_add_u64 v[8:9], s[14:15], 0, v[94:95]
	v_mov_b32_e32 v125, v95
	v_mov_b32_e32 v127, v95
	v_lshl_add_u64 v[4:5], v[8:9], 0, v[124:125]
	v_lshl_add_u64 v[10:11], v[98:99], 2, s[16:17]
	v_lshl_add_u64 v[12:13], v[100:101], 2, s[16:17]
	v_lshl_add_u64 v[14:15], v[102:103], 2, s[16:17]
	v_lshl_add_u64 v[8:9], v[8:9], 0, v[126:127]
	s_nop 0
	v_lshl_add_u64 v[16:17], v[104:105], 2, s[16:17]
	v_lshl_add_u64 v[8:9], v[108:109], 2, s[16:17]
	v_lshl_add_u64 v[10:11], v[110:111], 2, s[16:17]
	v_lshl_add_u64 v[12:13], v[112:113], 2, s[16:17]
	v_lshl_add_u64 v[14:15], v[114:115], 2, s[16:17]
	s_ashr_i32 s14, s12, 3
	s_lshl_b64 s[16:17], s[12:13], 19
	s_add_u32 s18, s3, s16
	s_addc_u32 s19, s11, s17
	v_mov_b32_e32 v149, v95
	v_lshl_add_u64 v[8:9], s[18:19], 0, v[148:149]
	s_ashr_i32 s15, s14, 31
	v_lshl_add_u64 v[16:17], s[18:19], 0, v[94:95]
	v_lshl_add_u64 v[18:19], v[8:9], 0, s[8:9]
	s_lshl_b64 s[16:17], s[14:15], 11
	v_lshl_add_u64 v[12:13], v[16:17], 0, v[124:125]
	v_lshl_add_u64 v[24:25], v[18:19], 0, v[124:125]
	global_load_dwordx4 v[8:11], v246, s[18:19]
	s_nop 0
	v_or_b32_e32 v27, s16, v96
	global_load_dwordx2 v[196:197], v[24:25], off
	v_mov_b64_e32 v[24:25], s[94:95]
	v_lshl_add_u32 v26, s38, 6, v92
	v_mad_u64_u32 v[24:25], s[18:19], v27, s35, v[24:25]
	v_mad_i32_i24 v25, s17, v147, v25
	v_lshlrev_b32_e32 v150, 1, v26
	v_mov_b32_e32 v151, v95
	v_lshl_add_u64 v[24:25], v[24:25], 0, v[150:151]
	global_load_dwordx2 v[174:175], v[24:25], off offset:2048
	v_mov_b32_e32 v170, v95
	v_mov_b32_e32 v171, v95
	s_and_saveexec_b64 s[18:19], s[4:5]
	s_cbranch_execz .LBB0_278
	v_add_co_u32_e32 v28, vcc, 0xfffff000, v24
	s_nop 1
	v_addc_co_u32_e32 v29, vcc, -1, v25, vcc
	global_load_dwordx2 v[170:171], v[28:29], off offset:-1024

.LBB0_279:
	s_or_b64 exec, exec, s[22:23]
	s_waitcnt lgkmcnt(0)
	s_barrier
	v_mov_b32_dpp v170, v174 row_shr:1 row_mask:0xf bank_mask:0xf
	v_mov_b32_dpp v171, v175 row_shr:1 row_mask:0xf bank_mask:0xf
	v_mov_b32_dpp v164, v174 row_ror:1 row_mask:0xf bank_mask:0xf
	v_mov_b32_dpp v165, v175 row_ror:1 row_mask:0xf bank_mask:0xf
	v_mov_b32_dpp v164, v168 row_shr:1 row_mask:0xf bank_mask:0xf
	v_mov_b32_dpp v165, v169 row_shr:1 row_mask:0xf bank_mask:0xf
	ds_read2st64_b64 v[20:23], v141 offset0:36 offset1:37
	s_waitcnt lgkmcnt(1)
	ds_read2st64_b64 v[36:39], v141 offset0:38 offset1:39
	v_lshlrev_b32_e32 v42, 16, v176
	v_and_b32_e32 v43, 0xffff0000, v176
	v_lshlrev_b32_e32 v40, 16, v174
	s_waitcnt lgkmcnt(1)
	v_pk_add_f32 v[20:21], v[20:21], 0 op_sel_hi:[1,0]
	v_and_b32_e32 v41, 0xffff0000, v174
	v_pk_add_f32 v[20:21], v[20:21], v[22:23]
	v_mul_f32_e32 v23, 0xbfb8aa3b, v42
	s_waitcnt lgkmcnt(0)
	v_pk_add_f32 v[20:21], v[20:21], v[36:37]
	v_exp_f32_e32 v23, v23
	v_pk_add_f32 v[20:21], v[20:21], v[38:39]
	v_lshlrev_b32_e32 v36, 16, v170
	v_pk_mul_f32 v[20:21], v[20:21], s[10:11] op_sel_hi:[1,0]
	v_add_f32_e32 v23, 1.0, v23
	v_fma_f32 v22, -v20, v20, v21
	v_max_f32_e32 v22, 0, v22
	v_add_f32_e32 v22, 0x3a27c5ac, v22
	v_rcp_f32_e32 v38, v23
	v_mul_f32_e32 v23, 0xbfb8aa3b, v43
	v_rsq_f32_e32 v22, v22
	v_exp_f32_e32 v23, v23
	v_and_b32_e32 v37, 0xffff0000, v170
	v_pk_add_f32 v[56:57], v[198:199], v[20:21] op_sel_hi:[1,0] neg_lo:[0,1] neg_hi:[0,1]
	v_pk_add_f32 v[36:37], v[36:37], v[40:41] neg_lo:[0,1] neg_hi:[0,1]
	v_pk_mul_f32 v[56:57], v[56:57], v[22:23] op_sel_hi:[1,0]
	v_add_f32_e32 v23, 1.0, v23
	s_waitcnt vmcnt(13)
	v_pk_fma_f32 v[36:37], v[36:37], v[232:233], v[40:41]
	v_lshlrev_b32_e32 v40, 16, v177
	v_rcp_f32_e32 v39, v23
	v_mul_f32_e32 v23, 0xbfb8aa3b, v40
	v_exp_f32_e32 v23, v23
	v_pk_fma_f32 v[56:57], v[228:229], v[56:57], v[250:251]
	v_and_b32_e32 v41, 0xffff0000, v177
	v_pk_fma_f32 v[36:37], v[172:173], v[36:37], v[56:57] op_sel_hi:[0,1,1]
	v_add_f32_e32 v23, 1.0, v23
	v_rcp_f32_e32 v56, v23
	v_mul_f32_e32 v23, 0xbfb8aa3b, v41
	v_exp_f32_e32 v23, v23
	v_pk_add_f32 v[20:21], v[196:197], v[20:21] op_sel_hi:[1,0] neg_lo:[0,1] neg_hi:[0,1]
	v_pk_mul_f32 v[38:39], v[38:39], v[42:43]
	v_lshlrev_b32_e32 v42, 16, v171
	v_pk_mul_f32 v[20:21], v[20:21], v[22:23] op_sel_hi:[1,0]
	v_add_f32_e32 v22, 1.0, v23
	v_rcp_f32_e32 v57, v22
	v_pk_mul_f32 v[36:37], v[38:39], v[36:37]
	v_lshlrev_b32_e32 v38, 16, v175
	v_and_b32_e32 v39, 0xffff0000, v175
	v_and_b32_e32 v43, 0xffff0000, v171
	v_pk_add_f32 v[22:23], v[42:43], v[38:39] neg_lo:[0,1] neg_hi:[0,1]
	v_pk_fma_f32 v[20:21], v[230:231], v[20:21], v[252:253]
	v_pk_fma_f32 v[22:23], v[22:23], v[254:255], v[38:39]
	v_lshl_add_u64 v[42:43], v[160:161], 0, s[20:21]
	v_pk_fma_f32 v[20:21], v[172:173], v[22:23], v[20:21] op_sel_hi:[0,1,1]
	v_pk_mul_f32 v[22:23], v[56:57], v[40:41]
	v_cvt_pk_bf16_f32 v40, v36, v37
	v_pk_mul_f32 v[38:39], v[22:23], v[20:21]
	ds_read2st64_b64 v[20:23], v143 offset0:36 offset1:37
	v_cvt_pk_bf16_f32 v41, v38, v39
	ds_read2st64_b64 v[36:39], v143 offset0:38 offset1:39
	ds_write_b64 v243, v[40:41] offset:34816
	v_lshlrev_b32_e32 v40, 16, v164
	s_waitcnt lgkmcnt(1)
	v_pk_add_f32 v[20:21], v[20:21], 0 op_sel_hi:[1,0]
	v_and_b32_e32 v41, 0xffff0000, v164
	v_pk_add_f32 v[20:21], v[20:21], v[22:23]
	s_waitcnt lgkmcnt(0)
	v_pk_add_f32 v[20:21], v[20:21], v[36:37]
	v_lshlrev_b32_e32 v36, 16, v168
	v_pk_add_f32 v[20:21], v[20:21], v[38:39]
	v_lshlrev_b32_e32 v38, 16, v166
	v_mul_f32_e32 v23, 0xbfb8aa3b, v38
	v_exp_f32_e32 v23, v23
	v_pk_mul_f32 v[20:21], v[20:21], s[10:11] op_sel_hi:[1,0]
	v_and_b32_e32 v39, 0xffff0000, v166
	v_fma_f32 v22, -v20, v20, v21
	v_max_f32_e32 v22, 0, v22
	v_add_f32_e32 v23, 1.0, v23
	v_add_f32_e32 v22, 0x3a27c5ac, v22
	v_rcp_f32_e32 v42, v23
	v_mul_f32_e32 v23, 0xbfb8aa3b, v39
	v_rsq_f32_e32 v22, v22
	v_exp_f32_e32 v23, v23
	v_and_b32_e32 v37, 0xffff0000, v168
	v_pk_add_f32 v[54:55], v[54:55], v[20:21] op_sel_hi:[1,0] neg_lo:[0,1] neg_hi:[0,1]
	v_pk_add_f32 v[40:41], v[40:41], v[36:37] neg_lo:[0,1] neg_hi:[0,1]
	v_pk_mul_f32 v[54:55], v[54:55], v[22:23] op_sel_hi:[1,0]
	v_add_f32_e32 v23, 1.0, v23
	v_pk_fma_f32 v[36:37], v[40:41], v[232:233], v[36:37]
	v_lshlrev_b32_e32 v40, 16, v167
	v_rcp_f32_e32 v43, v23
	v_mul_f32_e32 v23, 0xbfb8aa3b, v40
	v_exp_f32_e32 v23, v23
	v_pk_fma_f32 v[54:55], v[228:229], v[54:55], v[250:251]
	v_and_b32_e32 v41, 0xffff0000, v167
	v_pk_fma_f32 v[36:37], v[162:163], v[36:37], v[54:55] op_sel_hi:[0,1,1]
	v_add_f32_e32 v23, 1.0, v23
	v_rcp_f32_e32 v54, v23
	v_mul_f32_e32 v23, 0xbfb8aa3b, v41
	v_exp_f32_e32 v23, v23
	v_pk_add_f32 v[20:21], v[52:53], v[20:21] op_sel_hi:[1,0] neg_lo:[0,1] neg_hi:[0,1]
	v_pk_mul_f32 v[38:39], v[42:43], v[38:39]
	v_lshlrev_b32_e32 v42, 16, v165
	v_pk_mul_f32 v[20:21], v[20:21], v[22:23] op_sel_hi:[1,0]
	v_add_f32_e32 v22, 1.0, v23
	v_rcp_f32_e32 v55, v22
	v_pk_mul_f32 v[36:37], v[38:39], v[36:37]
	v_lshlrev_b32_e32 v38, 16, v169
	v_and_b32_e32 v39, 0xffff0000, v169
	v_and_b32_e32 v43, 0xffff0000, v165
	v_pk_add_f32 v[22:23], v[42:43], v[38:39] neg_lo:[0,1] neg_hi:[0,1]
	v_pk_fma_f32 v[20:21], v[230:231], v[20:21], v[252:253]
	v_pk_fma_f32 v[22:23], v[22:23], v[254:255], v[38:39]
	v_pk_fma_f32 v[20:21], v[162:163], v[22:23], v[20:21] op_sel_hi:[0,1,1]
	v_pk_mul_f32 v[22:23], v[54:55], v[40:41]
	v_pk_mul_f32 v[20:21], v[22:23], v[20:21]
	v_cvt_pk_bf16_f32 v22, v36, v37
	v_cvt_pk_bf16_f32 v23, v20, v21
	v_lshl_add_u64 v[20:21], v[158:159], 0, s[20:21]
	s_add_u32 s20, s20, 0x20000
	ds_write_b64 v243, v[22:23] offset:37120
	s_addc_u32 s21, s21, 0
	s_add_i32 s39, s39, 1
	s_waitcnt vmcnt(0)
	v_mov_b64_e32 v[164:165], v[192:193]
	s_cmp_eq_u32 s20, 0x400000
	v_mov_b64_e32 v[170:171], v[186:187]
	v_mov_b64_e32 v[166:167], v[190:191]
	v_mov_b64_e32 v[176:177], v[184:185]
	v_mov_b64_e32 v[174:175], v[182:183]
	v_mov_b64_e32 v[168:169], v[188:189]
	v_mov_b32_e32 v162, v127
	v_mov_b32_e32 v172, v125
	v_mov_b32_e32 v40, v216
	v_mov_b32_e32 v41, v217
	v_mov_b32_e32 v42, v218
	v_mov_b32_e32 v43, v219
	v_mov_b32_e32 v196, v178
	v_mov_b32_e32 v197, v179
	v_mov_b32_e32 v194, v180
	v_mov_b32_e32 v195, v181
	s_cbranch_scc1 .LBB0_268
.LBB0_280:
	s_cmp_lg_u32 s20, 0x3e0000
	s_cselect_b32 s15, s39, 31
	s_add_u32 s22, s18, s15
	s_addc_u32 s23, s19, 0
	s_mul_i32 s40, s23, 0x6000
	s_mul_hi_u32 s41, s22, 0x6000
	s_add_i32 s41, s41, s40
	s_mul_i32 s40, s22, 0x6000
	s_add_u32 s40, s86, s40
	s_addc_u32 s41, s87, s41
	s_waitcnt vmcnt(10)
	ds_write_b128 v246, v[0:3] offset:43008
	ds_write_b128 v246, v[8:11] offset:51200
	ds_write_b64 v242, v[182:183]
	ds_write_b64 v242, v[188:189] offset:576
	ds_write_b64 v242, v[184:185] offset:9216
	ds_write_b64 v242, v[190:191] offset:9792
	s_lshl_b64 s[100:101], s[22:23], 14
	s_add_u32 s100, s3, s100
	s_addc_u32 s101, s11, s101
	s_lshl_b64 s[22:23], s[22:23], 8
	s_add_u32 s22, s24, s22
	s_addc_u32 s23, s25, s23
	s_lshl_b32 s15, s15, 6
	s_waitcnt vmcnt(10)
	s_add_u32 s15, s16, s15
	v_mov_b32_e32 v76, v210
	v_mov_b32_e32 v77, v211
	v_mov_b32_e32 v78, v212
	v_mov_b32_e32 v79, v213
	s_sub_u32 s98, s15, 1
	s_mul_i32 s98, s98, 0x1c00
	s_add_u32 s98, s98, s94
	s_addc_u32 s99, s95, 0
	s_mov_b32 vcc_lo, 0x10001
	s_mov_b32 vcc_hi, 0x10001
	global_load_dwordx2 v[182:183], v240, s[98:99]
	global_load_dwordx2 v[188:189], v241, s[98:99]
	global_load_dwordx2 v[184:185], v240, s[98:99] offset:1280
	global_load_dwordx2 v[190:191], v241, s[98:99] offset:1280
	s_mov_b64 exec, vcc
	global_load_dwordx2 v[186:187], v245, s[98:99]
	s_mov_b64 exec, -1
	global_load_dword v125, v214, s[22:23]
	global_load_dword v127, v215, s[22:23]
	v_cvt_pk_bf16_f32 v80, v16, 0
	v_lshlrev_b32_e32 v81, 16, v80
	v_sub_f32_e32 v16, v16, v81
	v_cvt_pk_bf16_f32 v16, v16, s0
	ds_write_b16 v107, v80
	ds_write_b16 v107, v16 offset:9216
	v_cvt_pk_bf16_f32 v16, v17, 0
	v_lshlrev_b32_e32 v80, 16, v16
	v_sub_f32_e32 v17, v17, v80
	v_cvt_pk_bf16_f32 v17, v17, s0
	ds_write_b16 v107, v16 offset:144
	ds_write_b16 v107, v17 offset:9360
	v_cvt_pk_bf16_f32 v16, v18, 0
	v_lshlrev_b32_e32 v17, 16, v16
	v_sub_f32_e32 v17, v18, v17
	v_cvt_pk_bf16_f32 v17, v17, s0
	ds_write_b16 v107, v16 offset:288
	ds_write_b16 v107, v17 offset:9504
	v_cvt_pk_bf16_f32 v16, v19, 0
	v_lshlrev_b32_e32 v17, 16, v16
	v_sub_f32_e32 v17, v19, v17
	v_cvt_pk_bf16_f32 v17, v17, s0
	ds_write_b16 v107, v16 offset:432
	ds_write_b16 v107, v17 offset:9648
	v_cvt_pk_bf16_f32 v16, v32, 0
	v_lshlrev_b32_e32 v17, 16, v16
	v_sub_f32_e32 v17, v32, v17
	v_cvt_pk_bf16_f32 v17, v17, s0
	ds_write_b16 v135, v16
	ds_write_b16 v135, v17 offset:9216
	v_cvt_pk_bf16_f32 v16, v33, 0
	v_lshlrev_b32_e32 v17, 16, v16
	v_sub_f32_e32 v17, v33, v17
	v_cvt_pk_bf16_f32 v17, v17, s0
	ds_write_b16 v135, v16 offset:144
	ds_write_b16 v135, v17 offset:9360
	v_cvt_pk_bf16_f32 v16, v34, 0
	v_lshlrev_b32_e32 v17, 16, v16
	v_sub_f32_e32 v17, v34, v17
	v_cvt_pk_bf16_f32 v17, v17, s0
	ds_write_b16 v135, v16 offset:288
	ds_write_b16 v135, v17 offset:9504
	v_cvt_pk_bf16_f32 v16, v35, 0
	v_lshlrev_b32_e32 v17, 16, v16
	v_sub_f32_e32 v17, v35, v17
	v_cvt_pk_bf16_f32 v17, v17, s0
	ds_write_b16 v135, v16 offset:432
	ds_write_b16 v135, v17 offset:9648
	s_waitcnt lgkmcnt(0)
	s_barrier
	ds_read_b128 v[198:201], v247 offset:43008
	ds_read_b128 v[224:227], v247 offset:51200
	ds_read_b128 v[72:75], v247 offset:44032
	ds_read_b128 v[220:223], v247 offset:52224
	ds_read_b128 v[36:39], v247 offset:45056
	ds_read_b128 v[20:23], v247 offset:46080
	ds_read_b128 v[56:59], v247 offset:53248
	ds_read_b128 v[52:55], v247 offset:54272
	ds_read_b128 v[80:83], v139
	ds_read_b128 v[32:35], v139 offset:64
	s_waitcnt lgkmcnt(1)
	v_mfma_f32_16x16x32_bf16 v[16:19], v[80:83], v[198:201], v[76:79]
	ds_read_b128 v[84:87], v139 offset:9216
	s_nop 1
	ds_read_b128 v[76:79], v139 offset:9280
	s_waitcnt vmcnt(7)
	s_cmp_eq_u32 s39, 1
	s_cbranch_scc1 .Lmixst_skip
	s_lshl_b32 s42, s16, 11
	s_add_u32 s42, s42, s20
	s_add_u32 s42, s42, 0xde0000
	s_add_u32 s42, s96, s42
	s_addc_u32 s43, s97, 0
	ds_read_b64 v[24:25], v242 offset:34816
	ds_read_b64 v[26:27], v242 offset:35392
	s_waitcnt lgkmcnt(0)
	global_store_dwordx2 v234, v[24:25], s[42:43]
	global_store_dwordx2 v235, v[26:27], s[42:43]
.Lmixst_skip:
	v_lshlrev_b32_e32 v202, 16, v196
	v_and_b32_e32 v203, 0xffff0000, v196
	s_waitcnt lgkmcnt(1)
	v_mfma_f32_16x16x32_bf16 v[16:19], v[84:87], v[198:201], v[16:19]
	v_lshlrev_b32_e32 v196, 16, v197
	v_and_b32_e32 v197, 0xffff0000, v197
	v_and_b32_e32 v151, 64, v209
	v_mfma_f32_16x16x32_bf16 v[198:201], v[80:83], v[224:227], 0
	v_xor_b32_e32 v149, 16, v209
	v_add_u32_e32 v151, 64, v151
	v_cmp_lt_i32_e32 vcc, v149, v151
	v_mfma_f32_16x16x32_bf16 v[198:201], v[32:35], v[220:223], v[198:201]
	v_xor_b32_e32 v224, 32, v209
	v_cndmask_b32_e32 v149, v209, v149, vcc
	v_lshlrev_b32_e32 v149, 2, v149
	v_cmp_lt_i32_e32 vcc, v224, v151
	v_mfma_f32_16x16x32_bf16 v[16:19], v[32:35], v[72:75], v[16:19]
	global_load_dwordx4 v[0:3], v246, s[40:41]
	s_nop 2
	v_add_f32_e64 v198, v198, v202
	v_add_f32_e64 v199, v199, v203
	v_pk_add_f32 v[196:197], v[200:201], v[196:197]
	v_pk_mul_f32 v[200:201], v[198:199], v[198:199]
	v_pk_mul_f32 v[202:203], v[196:197], v[196:197]
	global_load_dwordx4 v[8:11], v246, s[100:101]
	v_mov_b32_e32 v220, v198
	v_mov_b32_e32 v221, v200
	v_mov_b32_e32 v200, v199
	v_pk_add_f32 v[200:201], v[220:221], v[200:201]
	v_mov_b32_e32 v220, v196
	v_mov_b32_e32 v221, v202
	v_mov_b32_e32 v202, v197
	v_pk_add_f32 v[202:203], v[220:221], v[202:203]
	v_cndmask_b32_e32 v151, v209, v224, vcc
	global_load_dwordx4 v[210:213], v236, s[40:41]
	v_pk_add_f32 v[200:201], v[200:201], v[202:203]
	ds_bpermute_b32 v202, v149, v200
	ds_bpermute_b32 v203, v149, v201
	v_lshlrev_b32_e32 v151, 2, v151
	global_load_dwordx4 v[216:219], v237, s[40:41]
	global_load_dwordx2 v[178:179], v238, s[100:101]
	global_load_dwordx2 v[180:181], v239, s[100:101]
	s_waitcnt lgkmcnt(2)
	v_mfma_f32_16x16x32_bf16 v[16:19], v[76:79], v[72:75], v[16:19]
	s_waitcnt lgkmcnt(0)
	v_pk_add_f32 v[200:201], v[200:201], v[202:203]
	ds_bpermute_b32 v202, v151, v200
	ds_bpermute_b32 v203, v151, v201
	s_and_saveexec_b64 s[22:23], s[30:31]
	s_cbranch_execz .LBB0_282
	s_waitcnt lgkmcnt(0)
	v_pk_add_f32 v[72:73], v[200:201], v[202:203]
	v_add_u32_e32 v74, s26, v130
	ds_write_b64 v74, v[72:73] offset:18432
